# v108 + one-time XCD-barrier census read batched (16 counter loads in flight, one wait) instead of 15 serialized round trips
# speedup vs baseline: 1.0027x; 1.0027x over previous
.LBB0_158:
	v_readlane_b32 s40, v253, 21
	v_readlane_b32 s41, v253, 22
	v_readlane_b32 s34, v252, 18
	s_mov_b64 s[42:43], -1
	s_nop 2
	global_load_dword v0, v17, s[40:41] sc1
	v_readlane_b32 s40, v253, 23
	v_readlane_b32 s41, v253, 24
	s_nop 4
	global_load_dword v1, v17, s[40:41] sc1
	v_readlane_b32 s40, v253, 25
	v_readlane_b32 s41, v253, 26
	s_nop 4
	global_load_dword v2, v17, s[40:41] sc1
	v_readlane_b32 s40, v253, 27
	v_readlane_b32 s41, v253, 28
	s_nop 4
	global_load_dword v3, v17, s[40:41] sc1
	v_readlane_b32 s40, v253, 29
	v_readlane_b32 s41, v253, 30
	s_nop 4
	global_load_dword v4, v17, s[40:41] sc1
	v_readlane_b32 s40, v253, 31
	v_readlane_b32 s41, v253, 32
	s_nop 4
	global_load_dword v5, v17, s[40:41] sc1
	v_readlane_b32 s40, v253, 33
	v_readlane_b32 s41, v253, 34
	s_nop 4
	global_load_dword v6, v17, s[40:41] sc1
	v_readlane_b32 s40, v253, 35
	v_readlane_b32 s41, v253, 36
	s_nop 4
	global_load_dword v7, v17, s[40:41] sc1
	v_readlane_b32 s40, v253, 37
	v_readlane_b32 s41, v253, 38
	s_nop 4
	global_load_dword v8, v17, s[40:41] sc1
	v_readlane_b32 s40, v253, 39
	v_readlane_b32 s41, v253, 40
	s_nop 4
	global_load_dword v9, v17, s[40:41] sc1
	v_readlane_b32 s40, v253, 41
	v_readlane_b32 s41, v253, 42
	s_nop 4
	global_load_dword v10, v17, s[40:41] sc1
	v_readlane_b32 s40, v253, 43
	v_readlane_b32 s41, v253, 44
	s_nop 4
	global_load_dword v11, v17, s[40:41] sc1
	v_readlane_b32 s40, v253, 45
	v_readlane_b32 s41, v253, 46
	s_nop 4
	global_load_dword v12, v17, s[40:41] sc1
	v_readlane_b32 s40, v253, 47
	v_readlane_b32 s41, v253, 48
	s_nop 4
	global_load_dword v13, v17, s[40:41] sc1
	v_readlane_b32 s40, v253, 49
	v_readlane_b32 s41, v253, 50
	s_nop 4
	global_load_dword v14, v17, s[40:41] sc1
	v_readlane_b32 s40, v253, 51
	v_readlane_b32 s41, v253, 52
	s_nop 4
	global_load_dword v15, v17, s[40:41] sc1
	s_mov_b64 s[40:41], -1
	s_waitcnt vmcnt(0)
	v_add_u32_e32 v16, v1, v0
	v_add_u32_e32 v16, v16, v2
	v_add_u32_e32 v16, v16, v3
	v_add_u32_e32 v16, v16, v4
	v_add_u32_e32 v16, v16, v5
	v_add_u32_e32 v16, v16, v6
	v_add_u32_e32 v16, v16, v7
	v_add_u32_e32 v16, v16, v8
	v_add_u32_e32 v16, v16, v9
	v_add_u32_e32 v16, v16, v10
	v_add_u32_e32 v16, v16, v11
	v_add_u32_e32 v16, v16, v12
	v_add_u32_e32 v16, v16, v13
	v_add_u32_e32 v16, v16, v14
	v_add_u32_e32 v16, v16, v15
	v_cmp_eq_u32_e32 vcc, s34, v16
	s_cbranch_vccnz .LBB0_157
	s_and_b32 s34, s25, 0xff
	s_cmp_eq_u32 s34, 0
	s_mov_b64 s[44:45], -1
	s_sleep 1
	s_cbranch_scc0 .LBB0_162
	v_readlane_b32 s40, v253, 19
	v_readlane_b32 s41, v253, 20
	s_nop 4
	global_load_dword v16, v17, s[40:41] sc1
	s_waitcnt vmcnt(0)
	v_cmp_eq_u32_e32 vcc, 0, v16
	s_cbranch_vccnz .LBB0_164
	s_mov_b64 s[44:45], 0
	s_mov_b64 s[40:41], -1

.LBB0_292:
	v_readlane_b32 s42, v253, 21
	v_readlane_b32 s43, v253, 22
	v_readlane_b32 s44, v252, 18
	s_nop 3
	global_load_dword v0, v17, s[42:43] sc1
	v_readlane_b32 s42, v253, 23
	v_readlane_b32 s43, v253, 24
	s_nop 4
	global_load_dword v1, v17, s[42:43] sc1
	v_readlane_b32 s42, v253, 25
	v_readlane_b32 s43, v253, 26
	s_nop 4
	global_load_dword v2, v17, s[42:43] sc1
	v_readlane_b32 s42, v253, 27
	v_readlane_b32 s43, v253, 28
	s_nop 4
	global_load_dword v3, v17, s[42:43] sc1
	v_readlane_b32 s42, v253, 29
	v_readlane_b32 s43, v253, 30
	s_nop 4
	global_load_dword v4, v17, s[42:43] sc1
	v_readlane_b32 s42, v253, 31
	v_readlane_b32 s43, v253, 32
	s_nop 4
	global_load_dword v5, v17, s[42:43] sc1
	v_readlane_b32 s42, v253, 33
	v_readlane_b32 s43, v253, 34
	s_nop 4
	global_load_dword v6, v17, s[42:43] sc1
	v_readlane_b32 s42, v253, 35
	v_readlane_b32 s43, v253, 36
	s_nop 4
	global_load_dword v7, v17, s[42:43] sc1
	v_readlane_b32 s42, v253, 37
	v_readlane_b32 s43, v253, 38
	s_nop 4
	global_load_dword v8, v17, s[42:43] sc1
	v_readlane_b32 s42, v253, 39
	v_readlane_b32 s43, v253, 40
	s_nop 4
	global_load_dword v9, v17, s[42:43] sc1
	v_readlane_b32 s42, v253, 41
	v_readlane_b32 s43, v253, 42
	s_nop 4
	global_load_dword v10, v17, s[42:43] sc1
	v_readlane_b32 s42, v253, 43
	v_readlane_b32 s43, v253, 44
	s_nop 4
	global_load_dword v11, v17, s[42:43] sc1
	v_readlane_b32 s42, v253, 45
	v_readlane_b32 s43, v253, 46
	s_nop 4
	global_load_dword v12, v17, s[42:43] sc1
	v_readlane_b32 s42, v253, 47
	v_readlane_b32 s43, v253, 48
	s_nop 4
	global_load_dword v13, v17, s[42:43] sc1
	v_readlane_b32 s42, v253, 49
	v_readlane_b32 s43, v253, 50
	s_nop 4
	global_load_dword v14, v17, s[42:43] sc1
	v_readlane_b32 s42, v253, 51
	v_readlane_b32 s43, v253, 52
	s_nop 4
	global_load_dword v15, v17, s[42:43] sc1
	s_mov_b64 s[42:43], -1
	s_waitcnt vmcnt(0)
	v_add_u32_e32 v16, v1, v0
	v_add_u32_e32 v16, v16, v2
	v_add_u32_e32 v16, v16, v3
	v_add_u32_e32 v16, v16, v4
	v_add_u32_e32 v16, v16, v5
	v_add_u32_e32 v16, v16, v6
	v_add_u32_e32 v16, v16, v7
	v_add_u32_e32 v16, v16, v8
	v_add_u32_e32 v16, v16, v9
	v_add_u32_e32 v16, v16, v10
	v_add_u32_e32 v16, v16, v11
	v_add_u32_e32 v16, v16, v12
	v_add_u32_e32 v16, v16, v13
	v_add_u32_e32 v16, v16, v14
	v_add_u32_e32 v16, v16, v15
	v_cmp_eq_u32_e32 vcc, s44, v16
	s_mov_b64 s[44:45], -1
	s_cbranch_vccnz .LBB0_291
	s_and_b32 s42, s34, 0xff
	s_cmp_eq_u32 s42, 0
	s_mov_b64 s[42:43], -1
	s_mov_b64 s[46:47], -1
	s_sleep 1
	s_cbranch_scc0 .LBB0_296
	v_readlane_b32 s42, v253, 19
	v_readlane_b32 s43, v253, 20
	s_nop 4
	global_load_dword v16, v17, s[42:43] sc1
	s_waitcnt vmcnt(0)
	v_cmp_eq_u32_e32 vcc, 0, v16
	s_cbranch_vccnz .LBB0_298
	s_mov_b64 s[46:47], 0
	s_mov_b64 s[42:43], -1

.LBB0_490:
	v_readlane_b32 s42, v253, 21
	v_readlane_b32 s43, v253, 22
	v_readlane_b32 s34, v252, 18
	s_mov_b64 s[44:45], -1
	s_nop 2
	global_load_dword v0, v17, s[42:43] sc1
	v_readlane_b32 s42, v253, 23
	v_readlane_b32 s43, v253, 24
	s_nop 4
	global_load_dword v1, v17, s[42:43] sc1
	v_readlane_b32 s42, v253, 25
	v_readlane_b32 s43, v253, 26
	s_nop 4
	global_load_dword v2, v17, s[42:43] sc1
	v_readlane_b32 s42, v253, 27
	v_readlane_b32 s43, v253, 28
	s_nop 4
	global_load_dword v3, v17, s[42:43] sc1
	v_readlane_b32 s42, v253, 29
	v_readlane_b32 s43, v253, 30
	s_nop 4
	global_load_dword v4, v17, s[42:43] sc1
	v_readlane_b32 s42, v253, 31
	v_readlane_b32 s43, v253, 32
	s_nop 4
	global_load_dword v5, v17, s[42:43] sc1
	v_readlane_b32 s42, v253, 33
	v_readlane_b32 s43, v253, 34
	s_nop 4
	global_load_dword v6, v17, s[42:43] sc1
	v_readlane_b32 s42, v253, 35
	v_readlane_b32 s43, v253, 36
	s_nop 4
	global_load_dword v7, v17, s[42:43] sc1
	v_readlane_b32 s42, v253, 37
	v_readlane_b32 s43, v253, 38
	s_nop 4
	global_load_dword v8, v17, s[42:43] sc1
	v_readlane_b32 s42, v253, 39
	v_readlane_b32 s43, v253, 40
	s_nop 4
	global_load_dword v9, v17, s[42:43] sc1
	v_readlane_b32 s42, v253, 41
	v_readlane_b32 s43, v253, 42
	s_nop 4
	global_load_dword v10, v17, s[42:43] sc1
	v_readlane_b32 s42, v253, 43
	v_readlane_b32 s43, v253, 44
	s_nop 4
	global_load_dword v11, v17, s[42:43] sc1
	v_readlane_b32 s42, v253, 45
	v_readlane_b32 s43, v253, 46
	s_nop 4
	global_load_dword v12, v17, s[42:43] sc1
	v_readlane_b32 s42, v253, 47
	v_readlane_b32 s43, v253, 48
	s_nop 4
	global_load_dword v13, v17, s[42:43] sc1
	v_readlane_b32 s42, v253, 49
	v_readlane_b32 s43, v253, 50
	s_nop 4
	global_load_dword v14, v17, s[42:43] sc1
	v_readlane_b32 s42, v253, 51
	v_readlane_b32 s43, v253, 52
	s_nop 4
	global_load_dword v15, v17, s[42:43] sc1
	s_mov_b64 s[42:43], -1
	s_waitcnt vmcnt(0)
	v_add_u32_e32 v16, v1, v0
	v_add_u32_e32 v16, v16, v2
	v_add_u32_e32 v16, v16, v3
	v_add_u32_e32 v16, v16, v4
	v_add_u32_e32 v16, v16, v5
	v_add_u32_e32 v16, v16, v6
	v_add_u32_e32 v16, v16, v7
	v_add_u32_e32 v16, v16, v8
	v_add_u32_e32 v16, v16, v9
	v_add_u32_e32 v16, v16, v10
	v_add_u32_e32 v16, v16, v11
	v_add_u32_e32 v16, v16, v12
	v_add_u32_e32 v16, v16, v13
	v_add_u32_e32 v16, v16, v14
	v_add_u32_e32 v16, v16, v15
	v_cmp_eq_u32_e32 vcc, s34, v16
	s_cbranch_vccnz .LBB0_489
	s_and_b32 s34, s25, 0xff
	s_cmp_eq_u32 s34, 0
	s_mov_b64 s[46:47], -1
	s_sleep 1
	s_cbranch_scc0 .LBB0_494
	v_readlane_b32 s42, v253, 19
	v_readlane_b32 s43, v253, 20
	s_nop 4
	global_load_dword v16, v17, s[42:43] sc1
	s_waitcnt vmcnt(0)
	v_cmp_eq_u32_e32 vcc, 0, v16
	s_cbranch_vccnz .LBB0_496
	s_mov_b64 s[46:47], 0
	s_mov_b64 s[42:43], -1

.LBB0_893:
	v_readlane_b32 s40, v253, 21
	v_readlane_b32 s41, v253, 22
	v_readlane_b32 s34, v252, 18
	s_mov_b64 s[44:45], -1
	s_nop 2
	global_load_dword v0, v17, s[40:41] sc1
	v_readlane_b32 s40, v253, 23
	v_readlane_b32 s41, v253, 24
	s_nop 4
	global_load_dword v1, v17, s[40:41] sc1
	v_readlane_b32 s40, v253, 25
	v_readlane_b32 s41, v253, 26
	s_nop 4
	global_load_dword v2, v17, s[40:41] sc1
	v_readlane_b32 s40, v253, 27
	v_readlane_b32 s41, v253, 28
	s_nop 4
	global_load_dword v3, v17, s[40:41] sc1
	v_readlane_b32 s40, v253, 29
	v_readlane_b32 s41, v253, 30
	s_nop 4
	global_load_dword v4, v17, s[40:41] sc1
	v_readlane_b32 s40, v253, 31
	v_readlane_b32 s41, v253, 32
	s_nop 4
	global_load_dword v5, v17, s[40:41] sc1
	v_readlane_b32 s40, v253, 33
	v_readlane_b32 s41, v253, 34
	s_nop 4
	global_load_dword v6, v17, s[40:41] sc1
	v_readlane_b32 s40, v253, 35
	v_readlane_b32 s41, v253, 36
	s_nop 4
	global_load_dword v7, v17, s[40:41] sc1
	v_readlane_b32 s40, v253, 37
	v_readlane_b32 s41, v253, 38
	s_nop 4
	global_load_dword v8, v17, s[40:41] sc1
	v_readlane_b32 s40, v253, 39
	v_readlane_b32 s41, v253, 40
	s_nop 4
	global_load_dword v9, v17, s[40:41] sc1
	v_readlane_b32 s40, v253, 41
	v_readlane_b32 s41, v253, 42
	s_nop 4
	global_load_dword v10, v17, s[40:41] sc1
	v_readlane_b32 s40, v253, 43
	v_readlane_b32 s41, v253, 44
	s_nop 4
	global_load_dword v11, v17, s[40:41] sc1
	v_readlane_b32 s40, v253, 45
	v_readlane_b32 s41, v253, 46
	s_nop 4
	global_load_dword v12, v17, s[40:41] sc1
	v_readlane_b32 s40, v253, 47
	v_readlane_b32 s41, v253, 48
	s_nop 4
	global_load_dword v13, v17, s[40:41] sc1
	v_readlane_b32 s40, v253, 49
	v_readlane_b32 s41, v253, 50
	s_nop 4
	global_load_dword v14, v17, s[40:41] sc1
	v_readlane_b32 s40, v253, 51
	v_readlane_b32 s41, v253, 52
	s_nop 4
	global_load_dword v15, v17, s[40:41] sc1
	s_mov_b64 s[40:41], -1
	s_waitcnt vmcnt(0)
	v_add_u32_e32 v16, v1, v0
	v_add_u32_e32 v16, v16, v2
	v_add_u32_e32 v16, v16, v3
	v_add_u32_e32 v16, v16, v4
	v_add_u32_e32 v16, v16, v5
	v_add_u32_e32 v16, v16, v6
	v_add_u32_e32 v16, v16, v7
	v_add_u32_e32 v16, v16, v8
	v_add_u32_e32 v16, v16, v9
	v_add_u32_e32 v16, v16, v10
	v_add_u32_e32 v16, v16, v11
	v_add_u32_e32 v16, v16, v12
	v_add_u32_e32 v16, v16, v13
	v_add_u32_e32 v16, v16, v14
	v_add_u32_e32 v16, v16, v15
	v_cmp_eq_u32_e32 vcc, s34, v16
	s_cbranch_vccnz .LBB0_892
	s_and_b32 s34, s25, 0xff
	s_cmp_eq_u32 s34, 0
	s_mov_b64 s[46:47], -1
	s_sleep 1
	s_cbranch_scc0 .LBB0_897
	v_readlane_b32 s40, v253, 19
	v_readlane_b32 s41, v253, 20
	s_nop 4
	global_load_dword v16, v17, s[40:41] sc1
	s_waitcnt vmcnt(0)
	v_cmp_eq_u32_e32 vcc, 0, v16
	s_cbranch_vccnz .LBB0_899
	s_mov_b64 s[46:47], 0
	s_mov_b64 s[40:41], -1

.LBB0_1079:
	v_readlane_b32 s44, v253, 21
	v_readlane_b32 s45, v253, 22
	v_readlane_b32 s43, v252, 18
	s_mov_b64 s[46:47], -1
	s_nop 2
	global_load_dword v0, v17, s[44:45] sc1
	v_readlane_b32 s44, v253, 23
	v_readlane_b32 s45, v253, 24
	s_nop 4
	global_load_dword v1, v17, s[44:45] sc1
	v_readlane_b32 s44, v253, 25
	v_readlane_b32 s45, v253, 26
	s_nop 4
	global_load_dword v2, v17, s[44:45] sc1
	v_readlane_b32 s44, v253, 27
	v_readlane_b32 s45, v253, 28
	s_nop 4
	global_load_dword v3, v17, s[44:45] sc1
	v_readlane_b32 s44, v253, 29
	v_readlane_b32 s45, v253, 30
	s_nop 4
	global_load_dword v4, v17, s[44:45] sc1
	v_readlane_b32 s44, v253, 31
	v_readlane_b32 s45, v253, 32
	s_nop 4
	global_load_dword v5, v17, s[44:45] sc1
	v_readlane_b32 s44, v253, 33
	v_readlane_b32 s45, v253, 34
	s_nop 4
	global_load_dword v6, v17, s[44:45] sc1
	v_readlane_b32 s44, v253, 35
	v_readlane_b32 s45, v253, 36
	s_nop 4
	global_load_dword v7, v17, s[44:45] sc1
	v_readlane_b32 s44, v253, 37
	v_readlane_b32 s45, v253, 38
	s_nop 4
	global_load_dword v8, v17, s[44:45] sc1
	v_readlane_b32 s44, v253, 39
	v_readlane_b32 s45, v253, 40
	s_nop 4
	global_load_dword v9, v17, s[44:45] sc1
	v_readlane_b32 s44, v253, 41
	v_readlane_b32 s45, v253, 42
	s_nop 4
	global_load_dword v10, v17, s[44:45] sc1
	v_readlane_b32 s44, v253, 43
	v_readlane_b32 s45, v253, 44
	s_nop 4
	global_load_dword v11, v17, s[44:45] sc1
	v_readlane_b32 s44, v253, 45
	v_readlane_b32 s45, v253, 46
	s_nop 4
	global_load_dword v12, v17, s[44:45] sc1
	v_readlane_b32 s44, v253, 47
	v_readlane_b32 s45, v253, 48
	s_nop 4
	global_load_dword v13, v17, s[44:45] sc1
	v_readlane_b32 s44, v253, 49
	v_readlane_b32 s45, v253, 50
	s_nop 4
	global_load_dword v14, v17, s[44:45] sc1
	v_readlane_b32 s44, v253, 51
	v_readlane_b32 s45, v253, 52
	s_nop 4
	global_load_dword v15, v17, s[44:45] sc1
	s_mov_b64 s[44:45], -1
	s_waitcnt vmcnt(0)
	v_add_u32_e32 v16, v1, v0
	v_add_u32_e32 v16, v16, v2
	v_add_u32_e32 v16, v16, v3
	v_add_u32_e32 v16, v16, v4
	v_add_u32_e32 v16, v16, v5
	v_add_u32_e32 v16, v16, v6
	v_add_u32_e32 v16, v16, v7
	v_add_u32_e32 v16, v16, v8
	v_add_u32_e32 v16, v16, v9
	v_add_u32_e32 v16, v16, v10
	v_add_u32_e32 v16, v16, v11
	v_add_u32_e32 v16, v16, v12
	v_add_u32_e32 v16, v16, v13
	v_add_u32_e32 v16, v16, v14
	v_add_u32_e32 v16, v16, v15
	v_cmp_eq_u32_e32 vcc, s43, v16
	s_cbranch_vccnz .LBB0_1078
	s_and_b32 s43, s34, 0xff
	s_cmp_eq_u32 s43, 0
	s_mov_b64 s[48:49], -1
	s_sleep 1
	s_cbranch_scc0 .LBB0_1083
	v_readlane_b32 s44, v253, 19
	v_readlane_b32 s45, v253, 20
	s_nop 4
	global_load_dword v16, v17, s[44:45] sc1
	s_waitcnt vmcnt(0)
	v_cmp_eq_u32_e32 vcc, 0, v16
	s_cbranch_vccnz .LBB0_1085
	s_mov_b64 s[48:49], 0
	s_mov_b64 s[44:45], -1
